# P1 GEMM K-loop hand-scheduled: in-place accumulators, A fragment ring read 5 groups ahead, B double-buffered, barrier at group 12 with next-buffer reads and LDS-DMA under the last MFMAs
# speedup vs baseline: 1.2434x; 1.0448x over previous
.LBB0_200:
	s_andn2_b64 vcc, exec, s[0:1]
	s_cbranch_vccnz .LBB0_192
	s_xor_b64 s[0:1], s[8:9], -1
	v_mov_b32_e32 v128, v132
	s_and_b64 s[8:9], s[8:9], exec
	s_cselect_b32 s25, s54, s56
	v_mov_b32_e32 v2, v128
	s_cselect_b32 s26, s55, s57
	s_and_b64 s[8:9], s[90:91], exec
	s_waitcnt lgkmcnt(0)
	s_barrier
	s_cselect_b32 s26, s53, s26
	v_lshlrev_b32_e32 v3, 4, v2
	v_and_b32_e32 v4, 32, v2
	s_cselect_b32 s27, s52, s25
	s_lshl_b32 s78, s23, 8
	s_lshl_b32 s94, s24, 8
	v_bitop3_b32 v4, v3, v4, 48 bitop3:0x6c
	v_lshlrev_b32_e32 v5, 9, v2
	s_movk_i32 s23, 0x7800
	s_ashr_i32 s95, s94, 31
	v_and_or_b32 v4, v5, s23, v4
	v_bfe_i32 v5, v2, 6, 22
	v_bfe_u32 v2, v2, 27, 1
	v_ashrrev_i32_e32 v0, 6, v128
	s_lshl_b64 s[8:9], s[78:79], 11
	s_lshl_b64 s[24:25], s[94:95], 11
	v_add_u32_e32 v2, v5, v2
	s_add_u32 s8, s27, s8
	v_lshlrev_b32_e32 v129, 10, v0
	v_and_b32_e32 v6, 0x3fffffe, v2
	v_lshlrev_b32_e32 v2, 14, v2
	s_addc_u32 s9, s26, s9
	v_add_u32_e32 v130, 0x8000, v129
	v_sub_u32_e32 v5, v5, v6
	v_and_or_b32 v2, v2, s89, v4
	v_readfirstlane_b32 s23, v129
	s_add_u32 s10, s10, s24
	v_lshl_add_u32 v2, v5, 6, v2
	s_mov_b32 m0, s23
	v_readfirstlane_b32 s23, v130
	s_addc_u32 s11, s11, s25
	v_mov_b32_e32 v246, v2
	global_load_lds_dwordx4 v2, s[8:9]
	s_mov_b32 m0, s23
	v_add_u32_e32 v131, 0x2000, v129
	global_load_lds_dwordx4 v2, s[10:11]
	v_add_u32_e32 v2, 0x2000, v3
	v_ashrrev_i32_e32 v2, 10, v2
	v_lshrrev_b32_e32 v5, 31, v2
	v_add_u32_e32 v5, v2, v5
	v_and_b32_e32 v6, 0x3fffffe, v5
	v_lshlrev_b32_e32 v5, 14, v5
	v_sub_u32_e32 v2, v2, v6
	v_and_or_b32 v5, v5, s89, v4
	v_readfirstlane_b32 s23, v131
	v_add_u32_e32 v136, 0xa000, v129
	v_lshl_add_u32 v2, v2, 6, v5
	s_mov_b32 m0, s23
	v_readfirstlane_b32 s23, v136
	v_mov_b32_e32 v247, v2
	global_load_lds_dwordx4 v2, s[8:9]
	s_mov_b32 m0, s23
	v_add_u32_e32 v137, 0x4000, v129
	global_load_lds_dwordx4 v2, s[10:11]
	v_add_u32_e32 v2, 0x4000, v3
	v_ashrrev_i32_e32 v2, 10, v2
	v_lshrrev_b32_e32 v5, 31, v2
	v_add_u32_e32 v5, v2, v5
	v_and_b32_e32 v6, 0x3fffffe, v5
	v_lshlrev_b32_e32 v5, 14, v5
	v_sub_u32_e32 v2, v2, v6
	v_and_or_b32 v5, v5, s89, v4
	v_readfirstlane_b32 s23, v137
	v_add_u32_e32 v138, 0xc000, v129
	v_lshl_add_u32 v2, v2, 6, v5
	s_mov_b32 m0, s23
	v_readfirstlane_b32 s23, v138
	v_mov_b32_e32 v248, v2
	global_load_lds_dwordx4 v2, s[8:9]
	s_mov_b32 m0, s23
	v_add_u32_e32 v139, 0x6000, v129
	global_load_lds_dwordx4 v2, s[10:11]
	v_add_u32_e32 v2, 0x6000, v3
	v_ashrrev_i32_e32 v2, 10, v2
	v_lshrrev_b32_e32 v3, 31, v2
	v_add_u32_e32 v3, v2, v3
	v_and_b32_e32 v5, 0x3fffffe, v3
	v_lshlrev_b32_e32 v3, 14, v3
	v_sub_u32_e32 v2, v2, v5
	v_and_or_b32 v3, v3, s89, v4
	v_readfirstlane_b32 s23, v139
	v_add_u32_e32 v140, 0xe000, v129
	v_lshl_add_u32 v2, v2, 6, v3
	s_mov_b32 m0, s23
	v_readfirstlane_b32 s23, v140
	v_mov_b32_e32 v249, v2
	global_load_lds_dwordx4 v2, s[8:9]
	s_mov_b32 m0, s23
	v_and_b32_e32 v1, 15, v128
	global_load_lds_dwordx4 v2, s[10:11]
	v_readfirstlane_b32 s24, v129
	s_add_u32 s98, s8, 0x80
	s_addc_u32 s99, s9, 0
	s_add_u32 s100, s10, 0x80
	s_addc_u32 s101, s11, 0
	s_add_u32 m0, s24, 0x10400
	s_nop 0
	global_load_lds_dwordx4 v246, s[98:99]
	s_add_u32 m0, s24, 0x18400
	s_nop 0
	global_load_lds_dwordx4 v246, s[100:101]
	s_add_u32 m0, s24, 0x12400
	s_nop 0
	global_load_lds_dwordx4 v247, s[98:99]
	s_add_u32 m0, s24, 0x1a400
	s_nop 0
	global_load_lds_dwordx4 v247, s[100:101]
	s_add_u32 m0, s24, 0x14400
	s_nop 0
	global_load_lds_dwordx4 v248, s[98:99]
	s_add_u32 m0, s24, 0x1c400
	s_nop 0
	global_load_lds_dwordx4 v248, s[100:101]
	s_add_u32 m0, s24, 0x16400
	s_nop 0
	global_load_lds_dwordx4 v249, s[98:99]
	s_add_u32 m0, s24, 0x1e400
	s_nop 0
	global_load_lds_dwordx4 v249, s[100:101]
	s_add_u32 s98, s98, 0x80
	s_addc_u32 s99, s99, 0
	s_add_u32 s100, s100, 0x80
	s_addc_u32 s101, s101, 0
	v_and_b32_e32 v2, 48, v128
	v_lshlrev_b32_e32 v1, 6, v1
	v_lshlrev_b32_e32 v4, 2, v128
	v_or_b32_e32 v3, v1, v2
	v_and_b32_e32 v4, 32, v4
	v_lshlrev_b32_e32 v0, 13, v0
	v_bitop3_b32 v141, v3, s70, v4 bitop3:0xde
	v_and_b32_e32 v3, 0x6000, v0
	v_lshlrev_b32_e32 v0, 6, v128
	v_and_b32_e32 v142, 0xffffc000, v0
	v_and_b32_e32 v0, 0x3c0, v0
	s_waitcnt vmcnt(8)
	v_bitop3_b32 v5, v0, v4, v2 bitop3:0x36
	v_or_b32_e32 v0, v0, v2
	v_bitop3_b32 v1, v1, v4, v2 bitop3:0x36
	v_or_b32_e32 v143, 0x800, v142
	v_or_b32_e32 v6, 0x1000, v142
	v_or_b32_e32 v7, 0x1800, v142
	v_or_b32_e32 v8, 0x2000, v142
	v_or_b32_e32 v9, 0x2800, v142
	v_or_b32_e32 v10, 0x3000, v142
	v_or_b32_e32 v2, 0x3800, v142
	v_bitop3_b32 v144, v0, s70, v4 bitop3:0xde
	v_mov_b32_e32 v0, 0
	s_mov_b32 s23, 0
	s_mov_b64 s[66:67], 0
	v_add_u32_e32 v145, 0x10400, v129
	v_add_u32_e32 v146, 0x18400, v129
	v_add_u32_e32 v147, 0x12400, v129
	v_add_u32_e32 v148, 0x1a400, v129
	v_add_u32_e32 v149, 0x14400, v129
	v_add_u32_e32 v150, 0x1c400, v129
	v_add_u32_e32 v151, 0x16400, v129
	v_add_u32_e32 v152, 0x1e400, v129
	v_add_u32_e32 v153, v1, v3
	v_add_u32_e32 v154, v1, v142
	v_add_u32_e32 v155, v5, v143
	v_add_u32_e32 v156, v5, v6
	v_add_u32_e32 v157, v5, v7
	v_add_u32_e32 v158, v5, v8
	v_add_u32_e32 v159, v5, v9
	v_add_u32_e32 v160, v5, v10
	v_add_u32_e32 v161, v5, v2
	v_add_u32_e32 v162, v141, v3
	v_add_u32_e32 v163, v144, v6
	v_add_u32_e32 v164, v144, v7
	v_add_u32_e32 v165, v144, v8
	v_add_u32_e32 v166, v144, v9
	v_add_u32_e32 v167, v144, v10
	v_add_u32_e32 v168, v144, v2
	v_mov_b32_e32 v1, v0
	v_mov_b32_e32 v2, v0
	v_mov_b32_e32 v3, v0
	v_mov_b32_e32 v4, v0
	v_mov_b32_e32 v5, v0
	v_mov_b32_e32 v6, v0
	v_mov_b32_e32 v7, v0
	v_mov_b32_e32 v8, v0
	v_mov_b32_e32 v9, v0
	v_mov_b32_e32 v10, v0
	v_mov_b32_e32 v11, v0
	v_mov_b32_e32 v12, v0
	v_mov_b32_e32 v13, v0
	v_mov_b32_e32 v14, v0
	v_mov_b32_e32 v15, v0
	v_mov_b32_e32 v16, v0
	v_mov_b32_e32 v17, v0
	v_mov_b32_e32 v18, v0
	v_mov_b32_e32 v19, v0
	v_mov_b32_e32 v20, v0
	v_mov_b32_e32 v21, v0
	v_mov_b32_e32 v22, v0
	v_mov_b32_e32 v23, v0
	v_mov_b32_e32 v24, v0
	v_mov_b32_e32 v25, v0
	v_mov_b32_e32 v26, v0
	v_mov_b32_e32 v27, v0
	v_mov_b32_e32 v28, v0
	v_mov_b32_e32 v29, v0
	v_mov_b32_e32 v30, v0
	v_mov_b32_e32 v31, v0
	v_mov_b32_e32 v32, v0
	v_mov_b32_e32 v33, v0
	v_mov_b32_e32 v34, v0
	v_mov_b32_e32 v35, v0
	v_mov_b32_e32 v36, v0
	v_mov_b32_e32 v37, v0
	v_mov_b32_e32 v38, v0
	v_mov_b32_e32 v39, v0
	v_mov_b32_e32 v40, v0
	v_mov_b32_e32 v41, v0
	v_mov_b32_e32 v42, v0
	v_mov_b32_e32 v43, v0
	v_mov_b32_e32 v44, v0
	v_mov_b32_e32 v45, v0
	v_mov_b32_e32 v46, v0
	v_mov_b32_e32 v47, v0
	v_mov_b32_e32 v48, v0
	v_mov_b32_e32 v49, v0
	v_mov_b32_e32 v50, v0
	v_mov_b32_e32 v51, v0
	v_mov_b32_e32 v52, v0
	v_mov_b32_e32 v53, v0
	v_mov_b32_e32 v54, v0
	v_mov_b32_e32 v55, v0
	v_mov_b32_e32 v56, v0
	v_mov_b32_e32 v57, v0
	v_mov_b32_e32 v58, v0
	v_mov_b32_e32 v59, v0
	v_mov_b32_e32 v60, v0
	v_mov_b32_e32 v61, v0
	v_mov_b32_e32 v62, v0
	v_mov_b32_e32 v63, v0
	v_mov_b32_e32 v64, v0
	v_mov_b32_e32 v65, v0
	v_mov_b32_e32 v66, v0
	v_mov_b32_e32 v67, v0
	v_mov_b32_e32 v68, v0
	v_mov_b32_e32 v69, v0
	v_mov_b32_e32 v70, v0
	v_mov_b32_e32 v71, v0
	v_mov_b32_e32 v72, v0
	v_mov_b32_e32 v73, v0
	v_mov_b32_e32 v74, v0
	v_mov_b32_e32 v75, v0
	v_mov_b32_e32 v76, v0
	v_mov_b32_e32 v77, v0
	v_mov_b32_e32 v78, v0
	v_mov_b32_e32 v79, v0
	v_mov_b32_e32 v80, v0
	v_mov_b32_e32 v81, v0
	v_mov_b32_e32 v82, v0
	v_mov_b32_e32 v83, v0
	v_mov_b32_e32 v84, v0
	v_mov_b32_e32 v85, v0
	v_mov_b32_e32 v86, v0
	v_mov_b32_e32 v87, v0
	v_mov_b32_e32 v88, v0
	v_mov_b32_e32 v89, v0
	v_mov_b32_e32 v90, v0
	v_mov_b32_e32 v91, v0
	v_mov_b32_e32 v92, v0
	v_mov_b32_e32 v93, v0
	v_mov_b32_e32 v94, v0
	v_mov_b32_e32 v95, v0
	v_mov_b32_e32 v96, v0
	v_mov_b32_e32 v97, v0
	v_mov_b32_e32 v98, v0
	v_mov_b32_e32 v99, v0
	v_mov_b32_e32 v100, v0
	v_mov_b32_e32 v101, v0
	v_mov_b32_e32 v102, v0
	v_mov_b32_e32 v103, v0
	v_mov_b32_e32 v104, v0
	v_mov_b32_e32 v105, v0
	v_mov_b32_e32 v106, v0
	v_mov_b32_e32 v107, v0
	v_mov_b32_e32 v108, v0
	v_mov_b32_e32 v109, v0
	v_mov_b32_e32 v110, v0
	v_mov_b32_e32 v111, v0
	v_mov_b32_e32 v112, v0
	v_mov_b32_e32 v113, v0
	v_mov_b32_e32 v114, v0
	v_mov_b32_e32 v115, v0
	v_mov_b32_e32 v116, v0
	v_mov_b32_e32 v117, v0
	v_mov_b32_e32 v118, v0
	v_mov_b32_e32 v119, v0
	v_mov_b32_e32 v120, v0
	v_mov_b32_e32 v121, v0
	v_mov_b32_e32 v122, v0
	v_mov_b32_e32 v123, v0
	v_mov_b32_e32 v124, v0
	v_mov_b32_e32 v125, v0
	v_mov_b32_e32 v126, v0
	v_mov_b32_e32 v127, v0
	v_add_u32_e32 v170, v141, v142
	v_add_u32_e32 v171, v144, v143
	s_waitcnt vmcnt(8) lgkmcnt(0)
	s_barrier
	ds_read_b128 v[174:177], v153 offset:32768
	ds_read_b128 v[178:181], v153 offset:34816
	ds_read_b128 v[182:185], v153 offset:36864
	ds_read_b128 v[186:189], v153 offset:38912
	ds_read_b128 v[214:217], v154
	ds_read_b128 v[218:221], v155
	ds_read_b128 v[222:225], v156
	s_branch .LBB0_203
.LBB0_203:
	ds_read_b128 v[226:229], v157
	ds_read_b128 v[230:233], v158
	ds_read_b128 v[234:237], v159
	s_waitcnt lgkmcnt(5)
	v_mfma_f32_16x16x32_bf16 v[124:127], v[214:217], v[174:177], v[124:127]
	v_mfma_f32_16x16x32_bf16 v[120:123], v[214:217], v[178:181], v[120:123]
	v_mfma_f32_16x16x32_bf16 v[116:119], v[214:217], v[182:185], v[116:119]
	v_mfma_f32_16x16x32_bf16 v[112:115], v[214:217], v[186:189], v[112:115]
	ds_read_b128 v[238:241], v160
	s_waitcnt lgkmcnt(5)
	v_mfma_f32_16x16x32_bf16 v[108:111], v[218:221], v[174:177], v[108:111]
	v_mfma_f32_16x16x32_bf16 v[104:107], v[218:221], v[178:181], v[104:107]
	v_mfma_f32_16x16x32_bf16 v[100:103], v[218:221], v[182:185], v[100:103]
	v_mfma_f32_16x16x32_bf16 v[96:99], v[218:221], v[186:189], v[96:99]
	ds_read_b128 v[242:245], v161
	ds_read_b128 v[190:193], v153 offset:33792
	s_waitcnt lgkmcnt(6)
	v_mfma_f32_16x16x32_bf16 v[92:95], v[222:225], v[174:177], v[92:95]
	v_mfma_f32_16x16x32_bf16 v[88:91], v[222:225], v[178:181], v[88:91]
	v_mfma_f32_16x16x32_bf16 v[84:87], v[222:225], v[182:185], v[84:87]
	v_mfma_f32_16x16x32_bf16 v[80:83], v[222:225], v[186:189], v[80:83]
	ds_read_b128 v[214:217], v154 offset:1024
	ds_read_b128 v[194:197], v153 offset:35840
	s_waitcnt lgkmcnt(7)
	v_mfma_f32_16x16x32_bf16 v[76:79], v[226:229], v[174:177], v[76:79]
	v_mfma_f32_16x16x32_bf16 v[72:75], v[226:229], v[178:181], v[72:75]
	v_mfma_f32_16x16x32_bf16 v[68:71], v[226:229], v[182:185], v[68:71]
	v_mfma_f32_16x16x32_bf16 v[64:67], v[226:229], v[186:189], v[64:67]
	ds_read_b128 v[218:221], v155 offset:1024
	ds_read_b128 v[198:201], v153 offset:37888
	s_waitcnt lgkmcnt(8)
	v_mfma_f32_16x16x32_bf16 v[60:63], v[230:233], v[174:177], v[60:63]
	v_mfma_f32_16x16x32_bf16 v[56:59], v[230:233], v[178:181], v[56:59]
	v_mfma_f32_16x16x32_bf16 v[52:55], v[230:233], v[182:185], v[52:55]
	v_mfma_f32_16x16x32_bf16 v[48:51], v[230:233], v[186:189], v[48:51]
	ds_read_b128 v[222:225], v156 offset:1024
	ds_read_b128 v[210:213], v153 offset:39936
	s_waitcnt lgkmcnt(9)
	v_mfma_f32_16x16x32_bf16 v[44:47], v[234:237], v[174:177], v[44:47]
	v_mfma_f32_16x16x32_bf16 v[40:43], v[234:237], v[178:181], v[40:43]
	v_mfma_f32_16x16x32_bf16 v[36:39], v[234:237], v[182:185], v[36:39]
	v_mfma_f32_16x16x32_bf16 v[32:35], v[234:237], v[186:189], v[32:35]
	ds_read_b128 v[226:229], v157 offset:1024
	s_waitcnt lgkmcnt(9)
	v_mfma_f32_16x16x32_bf16 v[28:31], v[238:241], v[174:177], v[28:31]
	v_mfma_f32_16x16x32_bf16 v[24:27], v[238:241], v[178:181], v[24:27]
	v_mfma_f32_16x16x32_bf16 v[20:23], v[238:241], v[182:185], v[20:23]
	v_mfma_f32_16x16x32_bf16 v[16:19], v[238:241], v[186:189], v[16:19]
	ds_read_b128 v[230:233], v158 offset:1024
	s_waitcnt lgkmcnt(9)
	v_mfma_f32_16x16x32_bf16 v[12:15], v[242:245], v[174:177], v[12:15]
	v_mfma_f32_16x16x32_bf16 v[8:11], v[242:245], v[178:181], v[8:11]
	v_mfma_f32_16x16x32_bf16 v[4:7], v[242:245], v[182:185], v[4:7]
	v_mfma_f32_16x16x32_bf16 v[0:3], v[242:245], v[186:189], v[0:3]
	ds_read_b128 v[234:237], v159 offset:1024
	s_waitcnt lgkmcnt(3)
	v_mfma_f32_16x16x32_bf16 v[124:127], v[214:217], v[190:193], v[124:127]
	v_mfma_f32_16x16x32_bf16 v[120:123], v[214:217], v[194:197], v[120:123]
	v_mfma_f32_16x16x32_bf16 v[116:119], v[214:217], v[198:201], v[116:119]
	v_mfma_f32_16x16x32_bf16 v[112:115], v[214:217], v[210:213], v[112:115]
	ds_read_b128 v[238:241], v160 offset:1024
	v_mfma_f32_16x16x32_bf16 v[108:111], v[218:221], v[190:193], v[108:111]
	v_mfma_f32_16x16x32_bf16 v[104:107], v[218:221], v[194:197], v[104:107]
	v_mfma_f32_16x16x32_bf16 v[100:103], v[218:221], v[198:201], v[100:103]
	v_mfma_f32_16x16x32_bf16 v[96:99], v[218:221], v[210:213], v[96:99]
	ds_read_b128 v[242:245], v161 offset:1024
	v_mfma_f32_16x16x32_bf16 v[92:95], v[222:225], v[190:193], v[92:95]
	v_mfma_f32_16x16x32_bf16 v[88:91], v[222:225], v[194:197], v[88:91]
	v_mfma_f32_16x16x32_bf16 v[84:87], v[222:225], v[198:201], v[84:87]
	v_mfma_f32_16x16x32_bf16 v[80:83], v[222:225], v[210:213], v[80:83]
	s_waitcnt lgkmcnt(4)
	v_mfma_f32_16x16x32_bf16 v[76:79], v[226:229], v[190:193], v[76:79]
	v_mfma_f32_16x16x32_bf16 v[72:75], v[226:229], v[194:197], v[72:75]
	v_mfma_f32_16x16x32_bf16 v[68:71], v[226:229], v[198:201], v[68:71]
	v_mfma_f32_16x16x32_bf16 v[64:67], v[226:229], v[210:213], v[64:67]
	s_waitcnt lgkmcnt(0)
	s_waitcnt vmcnt(0)
	s_barrier
	ds_read_b128 v[174:177], v162 offset:32768
	ds_read_b128 v[178:181], v162 offset:34816
	ds_read_b128 v[182:185], v162 offset:36864
	ds_read_b128 v[186:189], v162 offset:38912
	ds_read_b128 v[214:217], v170
	ds_read_b128 v[218:221], v171
	ds_read_b128 v[222:225], v163
	s_cmp_gt_u32 s23, 13
	s_cbranch_scc1 .Lg1_nostage0
	s_add_u32 m0, s24, 0x0
	v_mfma_f32_16x16x32_bf16 v[60:63], v[230:233], v[190:193], v[60:63]
	global_load_lds_dwordx4 v246, s[98:99]
	s_add_u32 m0, s24, 0x8000
	v_mfma_f32_16x16x32_bf16 v[56:59], v[230:233], v[194:197], v[56:59]
	global_load_lds_dwordx4 v246, s[100:101]
	v_mfma_f32_16x16x32_bf16 v[52:55], v[230:233], v[198:201], v[52:55]
	v_mfma_f32_16x16x32_bf16 v[48:51], v[230:233], v[210:213], v[48:51]
	s_add_u32 m0, s24, 0x2000
	v_mfma_f32_16x16x32_bf16 v[44:47], v[234:237], v[190:193], v[44:47]
	global_load_lds_dwordx4 v247, s[98:99]
	s_add_u32 m0, s24, 0xa000
	v_mfma_f32_16x16x32_bf16 v[40:43], v[234:237], v[194:197], v[40:43]
	global_load_lds_dwordx4 v247, s[100:101]
	v_mfma_f32_16x16x32_bf16 v[36:39], v[234:237], v[198:201], v[36:39]
	v_mfma_f32_16x16x32_bf16 v[32:35], v[234:237], v[210:213], v[32:35]
	s_add_u32 m0, s24, 0x4000
	v_mfma_f32_16x16x32_bf16 v[28:31], v[238:241], v[190:193], v[28:31]
	global_load_lds_dwordx4 v248, s[98:99]
	s_add_u32 m0, s24, 0xc000
	v_mfma_f32_16x16x32_bf16 v[24:27], v[238:241], v[194:197], v[24:27]
	global_load_lds_dwordx4 v248, s[100:101]
	v_mfma_f32_16x16x32_bf16 v[20:23], v[238:241], v[198:201], v[20:23]
	v_mfma_f32_16x16x32_bf16 v[16:19], v[238:241], v[210:213], v[16:19]
	s_add_u32 m0, s24, 0x6000
	v_mfma_f32_16x16x32_bf16 v[12:15], v[242:245], v[190:193], v[12:15]
	global_load_lds_dwordx4 v249, s[98:99]
	s_add_u32 m0, s24, 0xe000
	v_mfma_f32_16x16x32_bf16 v[8:11], v[242:245], v[194:197], v[8:11]
	global_load_lds_dwordx4 v249, s[100:101]
	v_mfma_f32_16x16x32_bf16 v[4:7], v[242:245], v[198:201], v[4:7]
	v_mfma_f32_16x16x32_bf16 v[0:3], v[242:245], v[210:213], v[0:3]
	s_add_u32 s98, s98, 0x80
	s_addc_u32 s99, s99, 0
	s_add_u32 s100, s100, 0x80
	s_addc_u32 s101, s101, 0
	s_branch .Lg1_half1
.Lg1_nostage0:
	v_mfma_f32_16x16x32_bf16 v[60:63], v[230:233], v[190:193], v[60:63]
	v_mfma_f32_16x16x32_bf16 v[56:59], v[230:233], v[194:197], v[56:59]
	v_mfma_f32_16x16x32_bf16 v[52:55], v[230:233], v[198:201], v[52:55]
	v_mfma_f32_16x16x32_bf16 v[48:51], v[230:233], v[210:213], v[48:51]
	v_mfma_f32_16x16x32_bf16 v[44:47], v[234:237], v[190:193], v[44:47]
	v_mfma_f32_16x16x32_bf16 v[40:43], v[234:237], v[194:197], v[40:43]
	v_mfma_f32_16x16x32_bf16 v[36:39], v[234:237], v[198:201], v[36:39]
	v_mfma_f32_16x16x32_bf16 v[32:35], v[234:237], v[210:213], v[32:35]
	v_mfma_f32_16x16x32_bf16 v[28:31], v[238:241], v[190:193], v[28:31]
	v_mfma_f32_16x16x32_bf16 v[24:27], v[238:241], v[194:197], v[24:27]
	v_mfma_f32_16x16x32_bf16 v[20:23], v[238:241], v[198:201], v[20:23]
	v_mfma_f32_16x16x32_bf16 v[16:19], v[238:241], v[210:213], v[16:19]
	v_mfma_f32_16x16x32_bf16 v[12:15], v[242:245], v[190:193], v[12:15]
	v_mfma_f32_16x16x32_bf16 v[8:11], v[242:245], v[194:197], v[8:11]
	v_mfma_f32_16x16x32_bf16 v[4:7], v[242:245], v[198:201], v[4:7]
	v_mfma_f32_16x16x32_bf16 v[0:3], v[242:245], v[210:213], v[0:3]
.Lg1_half1:
	ds_read_b128 v[226:229], v164
	ds_read_b128 v[230:233], v165
	ds_read_b128 v[234:237], v166
	s_waitcnt lgkmcnt(5)
	v_mfma_f32_16x16x32_bf16 v[124:127], v[214:217], v[174:177], v[124:127]
	v_mfma_f32_16x16x32_bf16 v[120:123], v[214:217], v[178:181], v[120:123]
	v_mfma_f32_16x16x32_bf16 v[116:119], v[214:217], v[182:185], v[116:119]
	v_mfma_f32_16x16x32_bf16 v[112:115], v[214:217], v[186:189], v[112:115]
	ds_read_b128 v[238:241], v167
	s_waitcnt lgkmcnt(5)
	v_mfma_f32_16x16x32_bf16 v[108:111], v[218:221], v[174:177], v[108:111]
	v_mfma_f32_16x16x32_bf16 v[104:107], v[218:221], v[178:181], v[104:107]
	v_mfma_f32_16x16x32_bf16 v[100:103], v[218:221], v[182:185], v[100:103]
	v_mfma_f32_16x16x32_bf16 v[96:99], v[218:221], v[186:189], v[96:99]
	ds_read_b128 v[242:245], v168
	ds_read_b128 v[190:193], v162 offset:33792
	s_waitcnt lgkmcnt(6)
	v_mfma_f32_16x16x32_bf16 v[92:95], v[222:225], v[174:177], v[92:95]
	v_mfma_f32_16x16x32_bf16 v[88:91], v[222:225], v[178:181], v[88:91]
	v_mfma_f32_16x16x32_bf16 v[84:87], v[222:225], v[182:185], v[84:87]
	v_mfma_f32_16x16x32_bf16 v[80:83], v[222:225], v[186:189], v[80:83]
	ds_read_b128 v[214:217], v170 offset:1024
	ds_read_b128 v[194:197], v162 offset:35840
	s_waitcnt lgkmcnt(7)
	v_mfma_f32_16x16x32_bf16 v[76:79], v[226:229], v[174:177], v[76:79]
	v_mfma_f32_16x16x32_bf16 v[72:75], v[226:229], v[178:181], v[72:75]
	v_mfma_f32_16x16x32_bf16 v[68:71], v[226:229], v[182:185], v[68:71]
	v_mfma_f32_16x16x32_bf16 v[64:67], v[226:229], v[186:189], v[64:67]
	ds_read_b128 v[218:221], v171 offset:1024
	ds_read_b128 v[198:201], v162 offset:37888
	s_waitcnt lgkmcnt(8)
	v_mfma_f32_16x16x32_bf16 v[60:63], v[230:233], v[174:177], v[60:63]
	v_mfma_f32_16x16x32_bf16 v[56:59], v[230:233], v[178:181], v[56:59]
	v_mfma_f32_16x16x32_bf16 v[52:55], v[230:233], v[182:185], v[52:55]
	v_mfma_f32_16x16x32_bf16 v[48:51], v[230:233], v[186:189], v[48:51]
	ds_read_b128 v[222:225], v163 offset:1024
	ds_read_b128 v[210:213], v162 offset:39936
	s_waitcnt lgkmcnt(9)
	v_mfma_f32_16x16x32_bf16 v[44:47], v[234:237], v[174:177], v[44:47]
	v_mfma_f32_16x16x32_bf16 v[40:43], v[234:237], v[178:181], v[40:43]
	v_mfma_f32_16x16x32_bf16 v[36:39], v[234:237], v[182:185], v[36:39]
	v_mfma_f32_16x16x32_bf16 v[32:35], v[234:237], v[186:189], v[32:35]
	ds_read_b128 v[226:229], v164 offset:1024
	s_waitcnt lgkmcnt(9)
	v_mfma_f32_16x16x32_bf16 v[28:31], v[238:241], v[174:177], v[28:31]
	v_mfma_f32_16x16x32_bf16 v[24:27], v[238:241], v[178:181], v[24:27]
	v_mfma_f32_16x16x32_bf16 v[20:23], v[238:241], v[182:185], v[20:23]
	v_mfma_f32_16x16x32_bf16 v[16:19], v[238:241], v[186:189], v[16:19]
	ds_read_b128 v[230:233], v165 offset:1024
	s_waitcnt lgkmcnt(9)
	v_mfma_f32_16x16x32_bf16 v[12:15], v[242:245], v[174:177], v[12:15]
	v_mfma_f32_16x16x32_bf16 v[8:11], v[242:245], v[178:181], v[8:11]
	v_mfma_f32_16x16x32_bf16 v[4:7], v[242:245], v[182:185], v[4:7]
	v_mfma_f32_16x16x32_bf16 v[0:3], v[242:245], v[186:189], v[0:3]
	ds_read_b128 v[234:237], v166 offset:1024
	s_waitcnt lgkmcnt(3)
	v_mfma_f32_16x16x32_bf16 v[124:127], v[214:217], v[190:193], v[124:127]
	v_mfma_f32_16x16x32_bf16 v[120:123], v[214:217], v[194:197], v[120:123]
	v_mfma_f32_16x16x32_bf16 v[116:119], v[214:217], v[198:201], v[116:119]
	v_mfma_f32_16x16x32_bf16 v[112:115], v[214:217], v[210:213], v[112:115]
	ds_read_b128 v[238:241], v167 offset:1024
	v_mfma_f32_16x16x32_bf16 v[108:111], v[218:221], v[190:193], v[108:111]
	v_mfma_f32_16x16x32_bf16 v[104:107], v[218:221], v[194:197], v[104:107]
	v_mfma_f32_16x16x32_bf16 v[100:103], v[218:221], v[198:201], v[100:103]
	v_mfma_f32_16x16x32_bf16 v[96:99], v[218:221], v[210:213], v[96:99]
	ds_read_b128 v[242:245], v168 offset:1024
	v_mfma_f32_16x16x32_bf16 v[92:95], v[222:225], v[190:193], v[92:95]
	v_mfma_f32_16x16x32_bf16 v[88:91], v[222:225], v[194:197], v[88:91]
	v_mfma_f32_16x16x32_bf16 v[84:87], v[222:225], v[198:201], v[84:87]
	v_mfma_f32_16x16x32_bf16 v[80:83], v[222:225], v[210:213], v[80:83]
	s_waitcnt lgkmcnt(4)
	v_mfma_f32_16x16x32_bf16 v[76:79], v[226:229], v[190:193], v[76:79]
	v_mfma_f32_16x16x32_bf16 v[72:75], v[226:229], v[194:197], v[72:75]
	v_mfma_f32_16x16x32_bf16 v[68:71], v[226:229], v[198:201], v[68:71]
	v_mfma_f32_16x16x32_bf16 v[64:67], v[226:229], v[210:213], v[64:67]
	s_waitcnt lgkmcnt(0)
	s_waitcnt vmcnt(0)
	s_barrier
	s_cmp_gt_u32 s23, 13
	s_cbranch_scc1 .Lg1_last
	ds_read_b128 v[174:177], v153 offset:32768
	ds_read_b128 v[178:181], v153 offset:34816
	ds_read_b128 v[182:185], v153 offset:36864
	ds_read_b128 v[186:189], v153 offset:38912
	ds_read_b128 v[214:217], v154
	ds_read_b128 v[218:221], v155
	ds_read_b128 v[222:225], v156
	s_add_u32 m0, s24, 0x10400
	v_mfma_f32_16x16x32_bf16 v[60:63], v[230:233], v[190:193], v[60:63]
	global_load_lds_dwordx4 v246, s[98:99]
	s_add_u32 m0, s24, 0x18400
	v_mfma_f32_16x16x32_bf16 v[56:59], v[230:233], v[194:197], v[56:59]
	global_load_lds_dwordx4 v246, s[100:101]
	v_mfma_f32_16x16x32_bf16 v[52:55], v[230:233], v[198:201], v[52:55]
	v_mfma_f32_16x16x32_bf16 v[48:51], v[230:233], v[210:213], v[48:51]
	s_add_u32 m0, s24, 0x12400
	v_mfma_f32_16x16x32_bf16 v[44:47], v[234:237], v[190:193], v[44:47]
	global_load_lds_dwordx4 v247, s[98:99]
	s_add_u32 m0, s24, 0x1a400
	v_mfma_f32_16x16x32_bf16 v[40:43], v[234:237], v[194:197], v[40:43]
	global_load_lds_dwordx4 v247, s[100:101]
	v_mfma_f32_16x16x32_bf16 v[36:39], v[234:237], v[198:201], v[36:39]
	v_mfma_f32_16x16x32_bf16 v[32:35], v[234:237], v[210:213], v[32:35]
	s_add_u32 m0, s24, 0x14400
	v_mfma_f32_16x16x32_bf16 v[28:31], v[238:241], v[190:193], v[28:31]
	global_load_lds_dwordx4 v248, s[98:99]
	s_add_u32 m0, s24, 0x1c400
	v_mfma_f32_16x16x32_bf16 v[24:27], v[238:241], v[194:197], v[24:27]
	global_load_lds_dwordx4 v248, s[100:101]
	v_mfma_f32_16x16x32_bf16 v[20:23], v[238:241], v[198:201], v[20:23]
	v_mfma_f32_16x16x32_bf16 v[16:19], v[238:241], v[210:213], v[16:19]
	s_add_u32 m0, s24, 0x16400
	v_mfma_f32_16x16x32_bf16 v[12:15], v[242:245], v[190:193], v[12:15]
	global_load_lds_dwordx4 v249, s[98:99]
	s_add_u32 m0, s24, 0x1e400
	v_mfma_f32_16x16x32_bf16 v[8:11], v[242:245], v[194:197], v[8:11]
	global_load_lds_dwordx4 v249, s[100:101]
	v_mfma_f32_16x16x32_bf16 v[4:7], v[242:245], v[198:201], v[4:7]
	v_mfma_f32_16x16x32_bf16 v[0:3], v[242:245], v[210:213], v[0:3]
	s_add_u32 s98, s98, 0x80
	s_addc_u32 s99, s99, 0
	s_add_u32 s100, s100, 0x80
	s_addc_u32 s101, s101, 0
	s_add_i32 s23, s23, 2
	s_branch .LBB0_203
.Lg1_last:
	v_mfma_f32_16x16x32_bf16 v[60:63], v[230:233], v[190:193], v[60:63]
	v_mfma_f32_16x16x32_bf16 v[56:59], v[230:233], v[194:197], v[56:59]
	v_mfma_f32_16x16x32_bf16 v[52:55], v[230:233], v[198:201], v[52:55]
	v_mfma_f32_16x16x32_bf16 v[48:51], v[230:233], v[210:213], v[48:51]
	v_mfma_f32_16x16x32_bf16 v[44:47], v[234:237], v[190:193], v[44:47]
	v_mfma_f32_16x16x32_bf16 v[40:43], v[234:237], v[194:197], v[40:43]
	v_mfma_f32_16x16x32_bf16 v[36:39], v[234:237], v[198:201], v[36:39]
	v_mfma_f32_16x16x32_bf16 v[32:35], v[234:237], v[210:213], v[32:35]
	v_mfma_f32_16x16x32_bf16 v[28:31], v[238:241], v[190:193], v[28:31]
	v_mfma_f32_16x16x32_bf16 v[24:27], v[238:241], v[194:197], v[24:27]
	v_mfma_f32_16x16x32_bf16 v[20:23], v[238:241], v[198:201], v[20:23]
	v_mfma_f32_16x16x32_bf16 v[16:19], v[238:241], v[210:213], v[16:19]
	v_mfma_f32_16x16x32_bf16 v[12:15], v[242:245], v[190:193], v[12:15]
	v_mfma_f32_16x16x32_bf16 v[8:11], v[242:245], v[194:197], v[8:11]
	v_mfma_f32_16x16x32_bf16 v[4:7], v[242:245], v[198:201], v[4:7]
	v_mfma_f32_16x16x32_bf16 v[0:3], v[242:245], v[210:213], v[0:3]
	s_nop 15
	s_nop 15
